# GEMM1 K-loop: 3 of the 6 LDS-DMA issues of each SP2 load segment moved into the same wave's MFMA cluster (vmcnt(8)->(5)); + no entry grid.sync
# speedup vs baseline: 1.0030x; 1.0030x over previous
; #define PG8_STAGE(bufoff, gbase, voff) do { _Pragma("unroll") for (int _i = 0; _i < 2; ++_i) \
;         __builtin_amdgcn_global_load_lds((const unsigned*)((const char*)(gbase) + (voff)[_i]), (PG8_LAS unsigned*)(lds + (bufoff) + ldsw + _i * 8192), 16, 0, 0); } while (0)
; #define PG8_LDA(dst, b, h) do { _Pragma("unroll") for (int m = 0; m < 4; ++m) _Pragma("unroll") for (int k = 0; k < 2; ++k) dst[m][k] = *(const PG8_LAS bf16x8*)(lds + PG8_SA(b, h) + aoff + m * 2048 + k * 1024); } while (0)
; #define PG8_LDB(dst, b, h) do { _Pragma("unroll") for (int n = 0; n < 2; ++n) _Pragma("unroll") for (int k = 0; k < 2; ++k) dst[n][k] = *(const PG8_LAS bf16x8*)(lds + PG8_SB(b, h) + boff + n * 2048 + k * 1024); } while (0)
; #define PG8_MMA(ai, bj, At, Bt) do { __builtin_amdgcn_s_setprio(1); _Pragma("unroll") for (int m = 0; m < 4; ++m) _Pragma("unroll") for (int n = 0; n < 2; ++n) _Pragma("unroll") for (int k = 0; k < 2; ++k) \
;         acc[ai][bj][m][n] = __builtin_amdgcn_mfma_f32_16x16x32_bf16(Bt[n][k], At[m][k], acc[ai][bj][m][n], 0, 0, 0); __builtin_amdgcn_s_setprio(0); } while (0)
; #define PG8_WAIT_V(n) asm volatile("s_waitcnt vmcnt(" #n ")" ::: "memory")
; #define PG8_WAIT_L(n) asm volatile("s_waitcnt lgkmcnt(" #n ")" ::: "memory")
; #define PG8_BAR __builtin_amdgcn_s_barrier()
; #define PG8_SCHED __builtin_amdgcn_sched_barrier(0)
; template <class Epi, class Sched, bool ALIGN_EPI = false, bool SP2 = false>
; __device__ __forceinline__ void gemm_phase(PG8_LAS unsigned char* lds, const Gemm g, const Sched& S, const Epi& E) {
;     ...
;             PG8_LDB(B0, 0, 0); PG8_LDB(B1, 0, 1); PG8_SCHED; PG8_LDA(At, 0, 0); PG8_STAGE(PG8_SA(1, 1), a1 + hstep, voffA);
;             PG8_WAIT_V(8); PG8_WAIT_L(0); PG8_BAR; PG8_MMA(0, 0, At, B0); PG8_MMA(0, 1, At, B1); PG8_BAR; PG8_SCHED;
;             PG8_LDA(At, 0, 1); PG8_STAGE(PG8_SB(0, 0), b2, voffB); PG8_STAGE(PG8_SB(0, 1), b2 + hstep, voffB); PG8_STAGE(PG8_SA(0, 0), a2, voffA);
;             PG8_WAIT_V(8); PG8_WAIT_L(0); PG8_BAR; PG8_MMA(1, 0, At, B0); PG8_MMA(1, 1, At, B1); PG8_BAR; PG8_SCHED;
.LBB0_399:
	v_or_b32_e32 v142, 0x10000, v141
	v_add_u32_e32 v146, 0x10400, v141
	v_add_u32_e32 v150, 0x10800, v141
	v_add_u32_e32 v154, 0x10c00, v141
	v_or_b32_e32 v158, 0x14000, v141
	v_add_u32_e32 v162, 0x14400, v141
	v_add_u32_e32 v166, 0x14800, v141
	v_add_u32_e32 v170, 0x14c00, v141
	s_add_i32 s74, s62, 2
	ds_read_b128 v[142:145], v142
	ds_read_b128 v[146:149], v146
	ds_read_b128 v[150:153], v150
	ds_read_b128 v[154:157], v154
	ds_read_b128 v[158:161], v158
	ds_read_b128 v[162:165], v162
	ds_read_b128 v[166:169], v166
	ds_read_b128 v[170:173], v170
	s_add_u32 s75, s60, 0x80
	s_addc_u32 s63, s61, 0
	s_cmp_eq_u32 s68, s62
	s_cselect_b32 s62, s40, s75
	s_cselect_b32 s63, s41, s63
	s_cselect_b32 s77, s53, s73
	s_cselect_b32 s76, s52, s55
	v_lshl_add_u64 v[210:211], s[60:61], 0, v[136:137]
	s_add_i32 m0, s12, 0xc000
	ds_read_b128 v[174:177], v140
	ds_read_b128 v[178:181], v140 offset:1024
	ds_read_b128 v[182:185], v140 offset:2048
	ds_read_b128 v[186:189], v140 offset:3072
	ds_read_b128 v[190:193], v140 offset:4096
	ds_read_b128 v[202:205], v140 offset:5120
	ds_read_b128 v[206:209], v140 offset:6144
	ds_read_b128 v[230:233], v140 offset:7168
	global_load_lds_dwordx4 v[210:211], off
	v_lshl_add_u64 v[210:211], s[60:61], 0, v[138:139]
	s_add_i32 m0, s12, 0xe000
	s_nop 0
	global_load_lds_dwordx4 v[210:211], off
	s_waitcnt vmcnt(8)
	s_waitcnt lgkmcnt(0)
	s_barrier
	s_setprio 1
	s_waitcnt lgkmcnt(0)
	v_mfma_f32_16x16x32_bf16 v[126:129], v[142:145], v[174:177], v[126:129]
	v_mfma_f32_16x16x32_bf16 v[122:125], v[150:153], v[174:177], v[122:125]
	v_mfma_f32_16x16x32_bf16 v[118:121], v[142:145], v[182:185], v[118:121]
	v_mfma_f32_16x16x32_bf16 v[114:117], v[150:153], v[182:185], v[114:117]
	v_mfma_f32_16x16x32_bf16 v[110:113], v[142:145], v[190:193], v[110:113]
	v_mfma_f32_16x16x32_bf16 v[106:109], v[150:153], v[190:193], v[106:109]
	v_mfma_f32_16x16x32_bf16 v[102:105], v[142:145], v[206:209], v[102:105]
	v_mfma_f32_16x16x32_bf16 v[98:101], v[150:153], v[206:209], v[98:101]
	v_mfma_f32_16x16x32_bf16 v[126:129], v[146:149], v[178:181], v[126:129]
	v_mfma_f32_16x16x32_bf16 v[122:125], v[154:157], v[178:181], v[122:125]
	v_mfma_f32_16x16x32_bf16 v[118:121], v[146:149], v[186:189], v[118:121]
	v_mfma_f32_16x16x32_bf16 v[114:117], v[154:157], v[186:189], v[114:117]
	v_mfma_f32_16x16x32_bf16 v[110:113], v[146:149], v[202:205], v[110:113]
	v_mfma_f32_16x16x32_bf16 v[106:109], v[154:157], v[202:205], v[106:109]
	v_mfma_f32_16x16x32_bf16 v[102:105], v[146:149], v[230:233], v[102:105]
	v_mfma_f32_16x16x32_bf16 v[98:101], v[154:157], v[230:233], v[98:101]
	s_setprio 0
	s_setprio 1
	v_mfma_f32_16x16x32_bf16 v[68:71], v[158:161], v[174:177], v[68:71]
	v_mfma_f32_16x16x32_bf16 v[64:67], v[166:169], v[174:177], v[64:67]
	v_mfma_f32_16x16x32_bf16 v[60:63], v[158:161], v[182:185], v[60:63]
	v_mfma_f32_16x16x32_bf16 v[56:59], v[166:169], v[182:185], v[56:59]
	v_mfma_f32_16x16x32_bf16 v[52:55], v[158:161], v[190:193], v[52:55]
	v_mfma_f32_16x16x32_bf16 v[48:51], v[166:169], v[190:193], v[48:51]
	v_mfma_f32_16x16x32_bf16 v[44:47], v[158:161], v[206:209], v[44:47]
	v_mfma_f32_16x16x32_bf16 v[40:43], v[166:169], v[206:209], v[40:43]
	v_mfma_f32_16x16x32_bf16 v[68:71], v[162:165], v[178:181], v[68:71]
	v_mfma_f32_16x16x32_bf16 v[64:67], v[170:173], v[178:181], v[64:67]
	v_mfma_f32_16x16x32_bf16 v[60:63], v[162:165], v[186:189], v[60:63]
	v_mfma_f32_16x16x32_bf16 v[56:59], v[170:173], v[186:189], v[56:59]
	v_mfma_f32_16x16x32_bf16 v[52:55], v[162:165], v[202:205], v[52:55]
	v_mfma_f32_16x16x32_bf16 v[48:51], v[170:173], v[202:205], v[48:51]
	v_mfma_f32_16x16x32_bf16 v[44:47], v[162:165], v[230:233], v[44:47]
	v_mfma_f32_16x16x32_bf16 v[40:43], v[170:173], v[230:233], v[40:43]
	s_setprio 0
	s_barrier
	s_mov_b32 m0, s13
	v_lshl_add_u64 v[210:211], s[76:77], 0, v[96:97]
	v_lshl_add_u64 v[234:235], s[76:77], 0, v[130:131]
	s_add_u32 s76, s76, s42
	ds_read_b128 v[174:177], v140 offset:16384
	ds_read_b128 v[178:181], v140 offset:17408
	ds_read_b128 v[182:185], v140 offset:18432
	ds_read_b128 v[186:189], v140 offset:19456
	ds_read_b128 v[190:193], v140 offset:20480
	ds_read_b128 v[202:205], v140 offset:21504
	ds_read_b128 v[206:209], v140 offset:22528
	ds_read_b128 v[230:233], v140 offset:23552
	global_load_lds_dwordx4 v[210:211], off
	s_mov_b32 m0, s16
	s_addc_u32 s77, s77, s43
	global_load_lds_dwordx4 v[234:235], off
	v_lshl_add_u64 v[236:237], s[76:77], 0, v[96:97]
	s_mov_b32 m0, s17
	v_lshl_add_u64 v[238:239], s[76:77], 0, v[130:131]
	global_load_lds_dwordx4 v[236:237], off
	v_lshl_add_u64 v[240:241], s[62:63], 0, v[134:135]
	v_lshl_add_u64 v[242:243], s[62:63], 0, v[132:133]
	s_waitcnt vmcnt(5)
	s_waitcnt lgkmcnt(0)
	s_barrier
; #define PG8_STAGE(bufoff, gbase, voff) do { _Pragma("unroll") for (int _i = 0; _i < 2; ++_i) \
;         __builtin_amdgcn_global_load_lds((const unsigned*)((const char*)(gbase) + (voff)[_i]), (PG8_LAS unsigned*)(lds + (bufoff) + ldsw + _i * 8192), 16, 0, 0); } while (0)
; #define PG8_LDA(dst, b, h) do { _Pragma("unroll") for (int m = 0; m < 4; ++m) _Pragma("unroll") for (int k = 0; k < 2; ++k) dst[m][k] = *(const PG8_LAS bf16x8*)(lds + PG8_SA(b, h) + aoff + m * 2048 + k * 1024); } while (0)
; #define PG8_LDB(dst, b, h) do { _Pragma("unroll") for (int n = 0; n < 2; ++n) _Pragma("unroll") for (int k = 0; k < 2; ++k) dst[n][k] = *(const PG8_LAS bf16x8*)(lds + PG8_SB(b, h) + boff + n * 2048 + k * 1024); } while (0)
; #define PG8_MMA(ai, bj, At, Bt) do { __builtin_amdgcn_s_setprio(1); _Pragma("unroll") for (int m = 0; m < 4; ++m) _Pragma("unroll") for (int n = 0; n < 2; ++n) _Pragma("unroll") for (int k = 0; k < 2; ++k) \
;         acc[ai][bj][m][n] = __builtin_amdgcn_mfma_f32_16x16x32_bf16(Bt[n][k], At[m][k], acc[ai][bj][m][n], 0, 0, 0); __builtin_amdgcn_s_setprio(0); } while (0)
; #define PG8_WAIT_V(n) asm volatile("s_waitcnt vmcnt(" #n ")" ::: "memory")
; #define PG8_WAIT_L(n) asm volatile("s_waitcnt lgkmcnt(" #n ")" ::: "memory")
; #define PG8_BAR __builtin_amdgcn_s_barrier()
; #define PG8_SCHED __builtin_amdgcn_sched_barrier(0)
; template <class Epi, class Sched, bool ALIGN_EPI = false, bool SP2 = false>
; __device__ __forceinline__ void gemm_phase(PG8_LAS unsigned char* lds, const Gemm g, const Sched& S, const Epi& E) {
;     ...
;             PG8_WAIT_V(8); PG8_WAIT_L(0); PG8_BAR; PG8_MMA(1, 0, At, B0); PG8_MMA(1, 1, At, B1); PG8_BAR; PG8_SCHED;
;             PG8_LDB(B0, 1, 0); PG8_LDB(B1, 1, 1); PG8_SCHED; PG8_LDA(At, 1, 0); PG8_STAGE(PG8_SA(0, 1), a2 + hstep, voffA);
;             PG8_WAIT_V(8); PG8_WAIT_L(0); PG8_BAR; PG8_MMA(0, 0, At, B0); PG8_MMA(0, 1, At, B1); PG8_BAR; PG8_SCHED;
	s_setprio 1
	s_waitcnt lgkmcnt(0)
	v_mfma_f32_16x16x32_bf16 v[92:95], v[142:145], v[174:177], v[92:95]
	v_mfma_f32_16x16x32_bf16 v[88:91], v[150:153], v[174:177], v[88:91]
	v_mfma_f32_16x16x32_bf16 v[84:87], v[142:145], v[182:185], v[84:87]
	v_mfma_f32_16x16x32_bf16 v[80:83], v[150:153], v[182:185], v[80:83]
	v_mfma_f32_16x16x32_bf16 v[76:79], v[142:145], v[190:193], v[76:79]
	v_mfma_f32_16x16x32_bf16 v[72:75], v[150:153], v[190:193], v[72:75]
	v_mfma_f32_16x16x32_bf16 v[12:15], v[142:145], v[206:209], v[12:15]
	v_mfma_f32_16x16x32_bf16 v[8:11], v[150:153], v[206:209], v[8:11]
	s_mov_b32 m0, s20
	s_nop 0
	global_load_lds_dwordx4 v[238:239], off
	v_mfma_f32_16x16x32_bf16 v[92:95], v[146:149], v[178:181], v[92:95]
	v_mfma_f32_16x16x32_bf16 v[88:91], v[154:157], v[178:181], v[88:91]
	v_mfma_f32_16x16x32_bf16 v[84:87], v[146:149], v[186:189], v[84:87]
	v_mfma_f32_16x16x32_bf16 v[80:83], v[154:157], v[186:189], v[80:83]
	v_mfma_f32_16x16x32_bf16 v[76:79], v[146:149], v[202:205], v[76:79]
	v_mfma_f32_16x16x32_bf16 v[72:75], v[154:157], v[202:205], v[72:75]
	v_mfma_f32_16x16x32_bf16 v[12:15], v[146:149], v[230:233], v[12:15]
	v_mfma_f32_16x16x32_bf16 v[8:11], v[154:157], v[230:233], v[8:11]
	s_mov_b32 m0, s12
	s_nop 0
	global_load_lds_dwordx4 v[240:241], off
	s_setprio 0
	s_setprio 1
	v_mfma_f32_16x16x32_bf16 v[36:39], v[158:161], v[174:177], v[36:39]
	v_mfma_f32_16x16x32_bf16 v[32:35], v[166:169], v[174:177], v[32:35]
	v_mfma_f32_16x16x32_bf16 v[28:31], v[158:161], v[182:185], v[28:31]
	v_mfma_f32_16x16x32_bf16 v[24:27], v[166:169], v[182:185], v[24:27]
	v_mfma_f32_16x16x32_bf16 v[20:23], v[158:161], v[190:193], v[20:23]
	v_mfma_f32_16x16x32_bf16 v[16:19], v[166:169], v[190:193], v[16:19]
	v_mfma_f32_16x16x32_bf16 v[4:7], v[158:161], v[206:209], v[4:7]
	v_mfma_f32_16x16x32_bf16 v[0:3], v[166:169], v[206:209], v[0:3]
	s_mov_b32 m0, s21
	s_nop 0
	global_load_lds_dwordx4 v[242:243], off
	v_mfma_f32_16x16x32_bf16 v[36:39], v[162:165], v[178:181], v[36:39]
	v_mfma_f32_16x16x32_bf16 v[32:35], v[170:173], v[178:181], v[32:35]
	v_mfma_f32_16x16x32_bf16 v[28:31], v[162:165], v[186:189], v[28:31]
	v_mfma_f32_16x16x32_bf16 v[24:27], v[170:173], v[186:189], v[24:27]
	v_mfma_f32_16x16x32_bf16 v[20:23], v[162:165], v[202:205], v[20:23]
	v_mfma_f32_16x16x32_bf16 v[16:19], v[170:173], v[202:205], v[16:19]
	v_mfma_f32_16x16x32_bf16 v[4:7], v[162:165], v[230:233], v[4:7]
	v_mfma_f32_16x16x32_bf16 v[0:3], v[170:173], v[230:233], v[0:3]
	s_setprio 0
	s_barrier
	v_or_b32_e32 v142, 0x18000, v141
	v_add_u32_e32 v146, 0x18400, v141
	v_add_u32_e32 v150, 0x18800, v141
	v_add_u32_e32 v154, 0x18c00, v141
	v_or_b32_e32 v158, 0x1c000, v141
	v_add_u32_e32 v162, 0x1c400, v141
	v_add_u32_e32 v166, 0x1c800, v141
	v_add_u32_e32 v170, 0x1cc00, v141
	ds_read_b128 v[142:145], v142
	ds_read_b128 v[146:149], v146
	ds_read_b128 v[150:153], v150
	ds_read_b128 v[154:157], v154
	ds_read_b128 v[158:161], v158
	ds_read_b128 v[162:165], v162
	ds_read_b128 v[166:169], v166
	ds_read_b128 v[170:173], v170
	s_add_u32 s62, s62, s42
	s_addc_u32 s63, s63, s43
	s_mov_b32 m0, s22
	v_lshl_add_u64 v[244:245], s[62:63], 0, v[134:135]
	ds_read_b128 v[174:177], v140 offset:32768
	ds_read_b128 v[178:181], v140 offset:33792
	ds_read_b128 v[182:185], v140 offset:34816
	ds_read_b128 v[186:189], v140 offset:35840
	ds_read_b128 v[190:193], v140 offset:36864
	ds_read_b128 v[202:205], v140 offset:37888
	ds_read_b128 v[206:209], v140 offset:38912
	ds_read_b128 v[230:233], v140 offset:39936
	global_load_lds_dwordx4 v[244:245], off
	v_lshl_add_u64 v[244:245], s[62:63], 0, v[132:133]
	s_mov_b32 m0, s23
	s_nop 0
	global_load_lds_dwordx4 v[244:245], off
	s_waitcnt vmcnt(8)
	s_waitcnt lgkmcnt(0)
	s_barrier
; #define PG8_STAGE(bufoff, gbase, voff) do { _Pragma("unroll") for (int _i = 0; _i < 2; ++_i) \
;         __builtin_amdgcn_global_load_lds((const unsigned*)((const char*)(gbase) + (voff)[_i]), (PG8_LAS unsigned*)(lds + (bufoff) + ldsw + _i * 8192), 16, 0, 0); } while (0)
; #define PG8_LDA(dst, b, h) do { _Pragma("unroll") for (int m = 0; m < 4; ++m) _Pragma("unroll") for (int k = 0; k < 2; ++k) dst[m][k] = *(const PG8_LAS bf16x8*)(lds + PG8_SA(b, h) + aoff + m * 2048 + k * 1024); } while (0)
; #define PG8_MMA(ai, bj, At, Bt) do { __builtin_amdgcn_s_setprio(1); _Pragma("unroll") for (int m = 0; m < 4; ++m) _Pragma("unroll") for (int n = 0; n < 2; ++n) _Pragma("unroll") for (int k = 0; k < 2; ++k) \
;         acc[ai][bj][m][n] = __builtin_amdgcn_mfma_f32_16x16x32_bf16(Bt[n][k], At[m][k], acc[ai][bj][m][n], 0, 0, 0); __builtin_amdgcn_s_setprio(0); } while (0)
; #define PG8_WAIT_V(n) asm volatile("s_waitcnt vmcnt(" #n ")" ::: "memory")
; #define PG8_WAIT_L(n) asm volatile("s_waitcnt lgkmcnt(" #n ")" ::: "memory")
; #define PG8_BAR __builtin_amdgcn_s_barrier()
; #define PG8_SCHED __builtin_amdgcn_sched_barrier(0)
; template <class Epi, class Sched, bool ALIGN_EPI = false, bool SP2 = false>
; __device__ __forceinline__ void gemm_phase(PG8_LAS unsigned char* lds, const Gemm g, const Sched& S, const Epi& E) {
;     ...
;             PG8_WAIT_V(8); PG8_WAIT_L(0); PG8_BAR; PG8_MMA(0, 0, At, B0); PG8_MMA(0, 1, At, B1); PG8_BAR; PG8_SCHED;
;             PG8_LDA(At, 1, 1); PG8_STAGE(PG8_SB(1, 0), b3, voffB); PG8_STAGE(PG8_SB(1, 1), b3 + hstep, voffB); PG8_STAGE(PG8_SA(1, 0), a3, voffA);
;             PG8_WAIT_V(8); PG8_WAIT_L(0); PG8_BAR; PG8_MMA(1, 0, At, B0); PG8_MMA(1, 1, At, B1); PG8_BAR; PG8_SCHED;
	s_setprio 1
	s_waitcnt lgkmcnt(0)
	v_mfma_f32_16x16x32_bf16 v[126:129], v[142:145], v[174:177], v[126:129]
	v_mfma_f32_16x16x32_bf16 v[122:125], v[150:153], v[174:177], v[122:125]
	v_mfma_f32_16x16x32_bf16 v[118:121], v[142:145], v[182:185], v[118:121]
	v_mfma_f32_16x16x32_bf16 v[114:117], v[150:153], v[182:185], v[114:117]
	v_mfma_f32_16x16x32_bf16 v[110:113], v[142:145], v[190:193], v[110:113]
	v_mfma_f32_16x16x32_bf16 v[106:109], v[150:153], v[190:193], v[106:109]
	v_mfma_f32_16x16x32_bf16 v[102:105], v[142:145], v[206:209], v[102:105]
	v_mfma_f32_16x16x32_bf16 v[98:101], v[150:153], v[206:209], v[98:101]
	v_mfma_f32_16x16x32_bf16 v[126:129], v[146:149], v[178:181], v[126:129]
	v_mfma_f32_16x16x32_bf16 v[122:125], v[154:157], v[178:181], v[122:125]
	v_mfma_f32_16x16x32_bf16 v[118:121], v[146:149], v[186:189], v[118:121]
	v_mfma_f32_16x16x32_bf16 v[114:117], v[154:157], v[186:189], v[114:117]
	v_mfma_f32_16x16x32_bf16 v[110:113], v[146:149], v[202:205], v[110:113]
	v_mfma_f32_16x16x32_bf16 v[106:109], v[154:157], v[202:205], v[106:109]
	v_mfma_f32_16x16x32_bf16 v[102:105], v[146:149], v[230:233], v[102:105]
	v_mfma_f32_16x16x32_bf16 v[98:101], v[154:157], v[230:233], v[98:101]
	s_setprio 0
	s_setprio 1
	v_mfma_f32_16x16x32_bf16 v[68:71], v[158:161], v[174:177], v[68:71]
	v_mfma_f32_16x16x32_bf16 v[64:67], v[166:169], v[174:177], v[64:67]
	v_mfma_f32_16x16x32_bf16 v[60:63], v[158:161], v[182:185], v[60:63]
	v_mfma_f32_16x16x32_bf16 v[56:59], v[166:169], v[182:185], v[56:59]
	v_mfma_f32_16x16x32_bf16 v[52:55], v[158:161], v[190:193], v[52:55]
	v_mfma_f32_16x16x32_bf16 v[48:51], v[166:169], v[190:193], v[48:51]
	v_mfma_f32_16x16x32_bf16 v[44:47], v[158:161], v[206:209], v[44:47]
	v_mfma_f32_16x16x32_bf16 v[40:43], v[166:169], v[206:209], v[40:43]
	v_mfma_f32_16x16x32_bf16 v[68:71], v[162:165], v[178:181], v[68:71]
	v_mfma_f32_16x16x32_bf16 v[64:67], v[170:173], v[178:181], v[64:67]
	v_mfma_f32_16x16x32_bf16 v[60:63], v[162:165], v[186:189], v[60:63]
	v_mfma_f32_16x16x32_bf16 v[56:59], v[170:173], v[186:189], v[56:59]
	v_mfma_f32_16x16x32_bf16 v[52:55], v[162:165], v[202:205], v[52:55]
	v_mfma_f32_16x16x32_bf16 v[48:51], v[170:173], v[202:205], v[48:51]
	v_mfma_f32_16x16x32_bf16 v[44:47], v[162:165], v[230:233], v[44:47]
	v_mfma_f32_16x16x32_bf16 v[40:43], v[170:173], v[230:233], v[40:43]
	s_setprio 0
	s_barrier
	s_mov_b32 m0, s31
	v_lshl_add_u64 v[210:211], v[210:211], 0, s[8:9]
	ds_read_b128 v[174:177], v140 offset:49152
	ds_read_b128 v[178:181], v140 offset:50176
	ds_read_b128 v[182:185], v140 offset:51200
	ds_read_b128 v[186:189], v140 offset:52224
	ds_read_b128 v[190:193], v140 offset:53248
	ds_read_b128 v[202:205], v140 offset:54272
	ds_read_b128 v[206:209], v140 offset:55296
	ds_read_b128 v[230:233], v140 offset:56320
	global_load_lds_dwordx4 v[210:211], off
	v_lshl_add_u64 v[210:211], v[234:235], 0, s[8:9]
	s_mov_b32 m0, s34
	s_nop 0
	global_load_lds_dwordx4 v[210:211], off
	v_lshl_add_u64 v[210:211], v[236:237], 0, s[8:9]
	s_mov_b32 m0, s65
	s_nop 0
	global_load_lds_dwordx4 v[210:211], off
	s_waitcnt vmcnt(5)
	s_waitcnt lgkmcnt(0)
	s_barrier
	s_setprio 1
	s_waitcnt lgkmcnt(0)
	v_mfma_f32_16x16x32_bf16 v[92:95], v[142:145], v[174:177], v[92:95]
	v_mfma_f32_16x16x32_bf16 v[88:91], v[150:153], v[174:177], v[88:91]
	v_mfma_f32_16x16x32_bf16 v[84:87], v[142:145], v[182:185], v[84:87]
	v_mfma_f32_16x16x32_bf16 v[80:83], v[150:153], v[182:185], v[80:83]
	v_mfma_f32_16x16x32_bf16 v[76:79], v[142:145], v[190:193], v[76:79]
	v_mfma_f32_16x16x32_bf16 v[72:75], v[150:153], v[190:193], v[72:75]
	v_mfma_f32_16x16x32_bf16 v[12:15], v[142:145], v[206:209], v[12:15]
	v_mfma_f32_16x16x32_bf16 v[8:11], v[150:153], v[206:209], v[8:11]
	v_lshl_add_u64 v[210:211], v[238:239], 0, s[8:9]
	s_mov_b32 m0, s66
	s_nop 0
	global_load_lds_dwordx4 v[210:211], off
	v_mfma_f32_16x16x32_bf16 v[92:95], v[146:149], v[178:181], v[92:95]
	v_mfma_f32_16x16x32_bf16 v[88:91], v[154:157], v[178:181], v[88:91]
	v_mfma_f32_16x16x32_bf16 v[84:87], v[146:149], v[186:189], v[84:87]
	v_mfma_f32_16x16x32_bf16 v[80:83], v[154:157], v[186:189], v[80:83]
	v_mfma_f32_16x16x32_bf16 v[76:79], v[146:149], v[202:205], v[76:79]
	v_mfma_f32_16x16x32_bf16 v[72:75], v[154:157], v[202:205], v[72:75]
	v_mfma_f32_16x16x32_bf16 v[12:15], v[146:149], v[230:233], v[12:15]
	v_mfma_f32_16x16x32_bf16 v[8:11], v[154:157], v[230:233], v[8:11]
	v_lshl_add_u64 v[210:211], v[240:241], 0, s[8:9]
	s_mov_b32 m0, s36
	s_nop 0
	global_load_lds_dwordx4 v[210:211], off
	s_setprio 0
	s_setprio 1
	v_mfma_f32_16x16x32_bf16 v[36:39], v[158:161], v[174:177], v[36:39]
	v_mfma_f32_16x16x32_bf16 v[32:35], v[166:169], v[174:177], v[32:35]
	v_mfma_f32_16x16x32_bf16 v[28:31], v[158:161], v[182:185], v[28:31]
	v_mfma_f32_16x16x32_bf16 v[24:27], v[166:169], v[182:185], v[24:27]
	v_mfma_f32_16x16x32_bf16 v[20:23], v[158:161], v[190:193], v[20:23]
	v_mfma_f32_16x16x32_bf16 v[16:19], v[166:169], v[190:193], v[16:19]
	v_mfma_f32_16x16x32_bf16 v[4:7], v[158:161], v[206:209], v[4:7]
	v_mfma_f32_16x16x32_bf16 v[0:3], v[166:169], v[206:209], v[0:3]
	v_lshl_add_u64 v[210:211], v[242:243], 0, s[8:9]
	s_mov_b32 m0, s64
	s_nop 0
	global_load_lds_dwordx4 v[210:211], off
	v_mfma_f32_16x16x32_bf16 v[36:39], v[162:165], v[178:181], v[36:39]
	v_mfma_f32_16x16x32_bf16 v[32:35], v[170:173], v[178:181], v[32:35]
	v_mfma_f32_16x16x32_bf16 v[28:31], v[162:165], v[186:189], v[28:31]
	v_mfma_f32_16x16x32_bf16 v[24:27], v[170:173], v[186:189], v[24:27]
	v_mfma_f32_16x16x32_bf16 v[20:23], v[162:165], v[202:205], v[20:23]
	v_mfma_f32_16x16x32_bf16 v[16:19], v[170:173], v[202:205], v[16:19]
	v_mfma_f32_16x16x32_bf16 v[4:7], v[162:165], v[230:233], v[4:7]
	v_mfma_f32_16x16x32_bf16 v[0:3], v[170:173], v[230:233], v[0:3]
	s_setprio 0
	s_barrier
	s_add_u32 s60, s60, 0x100
	s_addc_u32 s61, s61, 0
	s_add_u32 s55, s55, 0x100
	s_addc_u32 s73, s73, 0
	s_cmp_ge_i32 s74, s67
	s_mov_b32 s62, s74
	s_cbranch_scc0 .LBB0_399
	s_and_b64 vcc, exec, s[50:51]
	s_cbranch_vccz .LBB0_410
